# vk, tw and the counted wait used as the non-DPP slot ahead of the LDS instructions (fewer nops)
# speedup vs baseline: 1.0064x; 1.0064x over previous
.LBB0_682:
	s_bitcmp1_b32 s30, 0
	s_cselect_b32 s6, 0xe000, 0
	s_add_i32 s6, s6, 0
	v_add_u32_e32 v90, s6, v58
	v_sub_u32_e32 v88, v90, v61
	v_add_u32_e32 v89, s6, v86
	ds_read_b128 v[4:7], v90 offset:0x4000
	ds_read_b128 v[8:11], v90 offset:0x0
	ds_read2st64_b32 v[108:109], v89 offset0:192 offset1:193
	ds_read2st64_b64 v[100:103], v88 offset0:64 offset1:65
	ds_read_b128 v[112:115], v90 offset:0x4200
	ds_read_b128 v[96:99], v90 offset:0x200
	ds_read_b128 v[120:123], v90 offset:0x4400
	ds_read_b128 v[124:127], v90 offset:0x400
	v_mov_b32_e32 v93, v91
	s_waitcnt lgkmcnt(5)
	v_pk_mul_f32 v[0:1], v[52:53], v[4:5] op_sel_hi:[0,1]
	v_pk_fma_f32 v[0:1], v[52:53], v[6:7], v[0:1] op_sel:[1,0,0]
	v_pk_mul_f32 v[10:11], v[108:109], v[10:11] op_sel_hi:[0,1]
	ds_read_b128 v[4:7], v90 offset:0x4600
	v_add_f32_dpp v0, v0, v0 quad_perm:[1,0,3,2] row_mask:0xf bank_mask:0xf bound_ctrl:1
	v_add_f32_dpp v1, v1, v1 quad_perm:[1,0,3,2] row_mask:0xf bank_mask:0xf bound_ctrl:1
	s_nop 0
	v_add_f32_dpp v0, v0, v0 quad_perm:[2,3,0,1] row_mask:0xf bank_mask:0xf bound_ctrl:1
	v_pk_fma_f32 v[54:55], v[52:53], v[8:9], v[10:11]
	ds_read_b128 v[8:11], v90 offset:0x600
	v_add_f32_dpp v0, v0, v0 row_half_mirror row_mask:0xf bank_mask:0xf bound_ctrl:1
	s_waitcnt lgkmcnt(4)
	ds_read2st64_b32 v[110:111], v89 offset0:194 offset1:195
	ds_read2st64_b64 v[104:107], v88 offset0:66 offset1:67
	v_add_f32_dpp v2, v0, v0 row_mirror row_mask:0xf bank_mask:0xf bound_ctrl:1
	v_add_f32_dpp v0, v0, v0 row_mirror row_mask:0xf bank_mask:0xf bound_ctrl:1
	s_nop 1
	v_permlane16_swap_b32_e32 v0, v2
	v_add_f32_e32 v0, v0, v2
	v_pk_fma_f32 v[52:53], v[100:101], v[0:1], v[54:55] op_sel_hi:[1,0,1]
	v_pk_mul_f32 v[118:119], v[52:53], v[112:113] op_sel_hi:[0,1]
	v_pk_fma_f32 v[118:119], v[52:53], v[114:115], v[118:119] op_sel:[1,0,0]
	v_pk_mul_f32 v[98:99], v[108:109], v[98:99] op_sel:[1,0]
	ds_read_b128 v[112:115], v90 offset:0x4800
	v_add_f32_dpp v118, v118, v118 quad_perm:[1,0,3,2] row_mask:0xf bank_mask:0xf bound_ctrl:1
	v_add_f32_dpp v119, v119, v119 quad_perm:[1,0,3,2] row_mask:0xf bank_mask:0xf bound_ctrl:1
	s_nop 0
	v_add_f32_dpp v118, v118, v118 quad_perm:[2,3,0,1] row_mask:0xf bank_mask:0xf bound_ctrl:1
	v_pk_fma_f32 v[54:55], v[52:53], v[96:97], v[98:99]
	ds_read_b128 v[96:99], v90 offset:0x800
	v_add_f32_dpp v118, v118, v118 row_half_mirror row_mask:0xf bank_mask:0xf bound_ctrl:1
	s_waitcnt lgkmcnt(3)
	ds_write2_b32 v93, v1, v119 offset0:0 offset1:36
	v_add_f32_dpp v2, v118, v118 row_mirror row_mask:0xf bank_mask:0xf bound_ctrl:1
	v_add_f32_dpp v118, v118, v118 row_mirror row_mask:0xf bank_mask:0xf bound_ctrl:1
	s_nop 1
	v_permlane16_swap_b32_e32 v118, v2
	v_add_f32_e32 v118, v118, v2
	v_pk_fma_f32 v[52:53], v[102:103], v[118:119], v[54:55] op_sel_hi:[1,0,1]
	v_pk_mul_f32 v[0:1], v[52:53], v[120:121] op_sel_hi:[0,1]
	v_pk_fma_f32 v[0:1], v[52:53], v[122:123], v[0:1] op_sel:[1,0,0]
	v_pk_mul_f32 v[126:127], v[110:111], v[126:127] op_sel_hi:[0,1]
	ds_read_b128 v[120:123], v90 offset:0x4a00
	v_add_f32_dpp v0, v0, v0 quad_perm:[1,0,3,2] row_mask:0xf bank_mask:0xf bound_ctrl:1
	v_add_f32_dpp v1, v1, v1 quad_perm:[1,0,3,2] row_mask:0xf bank_mask:0xf bound_ctrl:1
	s_nop 0
	v_add_f32_dpp v0, v0, v0 quad_perm:[2,3,0,1] row_mask:0xf bank_mask:0xf bound_ctrl:1
	v_pk_fma_f32 v[54:55], v[52:53], v[124:125], v[126:127]
	ds_read_b128 v[124:127], v90 offset:0xa00
	v_add_f32_dpp v0, v0, v0 row_half_mirror row_mask:0xf bank_mask:0xf bound_ctrl:1
	s_waitcnt lgkmcnt(5)
	ds_read2st64_b32 v[108:109], v89 offset0:196 offset1:197
	ds_read2st64_b64 v[100:103], v88 offset0:68 offset1:69
	v_add_f32_dpp v2, v0, v0 row_mirror row_mask:0xf bank_mask:0xf bound_ctrl:1
	v_add_f32_dpp v0, v0, v0 row_mirror row_mask:0xf bank_mask:0xf bound_ctrl:1
	s_nop 1
	v_permlane16_swap_b32_e32 v0, v2
	v_add_f32_e32 v0, v0, v2
	v_pk_fma_f32 v[52:53], v[104:105], v[0:1], v[54:55] op_sel_hi:[1,0,1]
	v_pk_mul_f32 v[118:119], v[52:53], v[4:5] op_sel_hi:[0,1]
	v_pk_fma_f32 v[118:119], v[52:53], v[6:7], v[118:119] op_sel:[1,0,0]
	v_pk_mul_f32 v[10:11], v[110:111], v[10:11] op_sel:[1,0]
	ds_read_b128 v[4:7], v90 offset:0x4c00
	v_add_f32_dpp v118, v118, v118 quad_perm:[1,0,3,2] row_mask:0xf bank_mask:0xf bound_ctrl:1
	v_add_f32_dpp v119, v119, v119 quad_perm:[1,0,3,2] row_mask:0xf bank_mask:0xf bound_ctrl:1
	s_nop 0
	v_add_f32_dpp v118, v118, v118 quad_perm:[2,3,0,1] row_mask:0xf bank_mask:0xf bound_ctrl:1
	v_pk_fma_f32 v[54:55], v[52:53], v[8:9], v[10:11]
	ds_read_b128 v[8:11], v90 offset:0xc00
	v_add_f32_dpp v118, v118, v118 row_half_mirror row_mask:0xf bank_mask:0xf bound_ctrl:1
	s_waitcnt lgkmcnt(3)
	ds_write2_b32 v93, v1, v119 offset0:72 offset1:108
	v_add_f32_dpp v2, v118, v118 row_mirror row_mask:0xf bank_mask:0xf bound_ctrl:1
	v_add_f32_dpp v118, v118, v118 row_mirror row_mask:0xf bank_mask:0xf bound_ctrl:1
	s_nop 1
	v_permlane16_swap_b32_e32 v118, v2
	v_add_f32_e32 v118, v118, v2
	v_pk_fma_f32 v[52:53], v[106:107], v[118:119], v[54:55] op_sel_hi:[1,0,1]
	v_pk_mul_f32 v[0:1], v[52:53], v[112:113] op_sel_hi:[0,1]
	v_pk_fma_f32 v[0:1], v[52:53], v[114:115], v[0:1] op_sel:[1,0,0]
	v_pk_mul_f32 v[98:99], v[108:109], v[98:99] op_sel_hi:[0,1]
	ds_read_b128 v[112:115], v90 offset:0x4e00
	v_add_f32_dpp v0, v0, v0 quad_perm:[1,0,3,2] row_mask:0xf bank_mask:0xf bound_ctrl:1
	v_add_f32_dpp v1, v1, v1 quad_perm:[1,0,3,2] row_mask:0xf bank_mask:0xf bound_ctrl:1
	s_nop 0
	v_add_f32_dpp v0, v0, v0 quad_perm:[2,3,0,1] row_mask:0xf bank_mask:0xf bound_ctrl:1
	v_pk_fma_f32 v[54:55], v[52:53], v[96:97], v[98:99]
	ds_read_b128 v[96:99], v90 offset:0xe00
	v_add_f32_dpp v0, v0, v0 row_half_mirror row_mask:0xf bank_mask:0xf bound_ctrl:1
	s_waitcnt lgkmcnt(5)
	ds_read2st64_b32 v[110:111], v89 offset0:198 offset1:199
	ds_read2st64_b64 v[104:107], v88 offset0:70 offset1:71
	v_add_f32_dpp v2, v0, v0 row_mirror row_mask:0xf bank_mask:0xf bound_ctrl:1
	v_add_f32_dpp v0, v0, v0 row_mirror row_mask:0xf bank_mask:0xf bound_ctrl:1
	s_nop 1
	v_permlane16_swap_b32_e32 v0, v2
	v_add_f32_e32 v0, v0, v2
	v_pk_fma_f32 v[52:53], v[100:101], v[0:1], v[54:55] op_sel_hi:[1,0,1]
	v_pk_mul_f32 v[118:119], v[52:53], v[120:121] op_sel_hi:[0,1]
	v_pk_fma_f32 v[118:119], v[52:53], v[122:123], v[118:119] op_sel:[1,0,0]
	v_pk_mul_f32 v[126:127], v[108:109], v[126:127] op_sel:[1,0]
	ds_read_b128 v[120:123], v90 offset:0x5000
	v_add_f32_dpp v118, v118, v118 quad_perm:[1,0,3,2] row_mask:0xf bank_mask:0xf bound_ctrl:1
	v_add_f32_dpp v119, v119, v119 quad_perm:[1,0,3,2] row_mask:0xf bank_mask:0xf bound_ctrl:1
	s_nop 0
	v_add_f32_dpp v118, v118, v118 quad_perm:[2,3,0,1] row_mask:0xf bank_mask:0xf bound_ctrl:1
	v_pk_fma_f32 v[54:55], v[52:53], v[124:125], v[126:127]
	ds_read_b128 v[124:127], v90 offset:0x1000
	v_add_f32_dpp v118, v118, v118 row_half_mirror row_mask:0xf bank_mask:0xf bound_ctrl:1
	s_waitcnt lgkmcnt(3)
	ds_write2_b32 v93, v1, v119 offset0:144 offset1:180
	v_add_f32_dpp v2, v118, v118 row_mirror row_mask:0xf bank_mask:0xf bound_ctrl:1
	v_add_f32_dpp v118, v118, v118 row_mirror row_mask:0xf bank_mask:0xf bound_ctrl:1
	s_nop 1
	v_permlane16_swap_b32_e32 v118, v2
	v_add_f32_e32 v118, v118, v2
	v_pk_fma_f32 v[52:53], v[102:103], v[118:119], v[54:55] op_sel_hi:[1,0,1]
	v_pk_mul_f32 v[0:1], v[52:53], v[4:5] op_sel_hi:[0,1]
	v_pk_fma_f32 v[0:1], v[52:53], v[6:7], v[0:1] op_sel:[1,0,0]
	v_pk_mul_f32 v[10:11], v[110:111], v[10:11] op_sel_hi:[0,1]
	ds_read_b128 v[4:7], v90 offset:0x5200
	v_add_f32_dpp v0, v0, v0 quad_perm:[1,0,3,2] row_mask:0xf bank_mask:0xf bound_ctrl:1
	v_add_f32_dpp v1, v1, v1 quad_perm:[1,0,3,2] row_mask:0xf bank_mask:0xf bound_ctrl:1
	s_nop 0
	v_add_f32_dpp v0, v0, v0 quad_perm:[2,3,0,1] row_mask:0xf bank_mask:0xf bound_ctrl:1
	v_pk_fma_f32 v[54:55], v[52:53], v[8:9], v[10:11]
	ds_read_b128 v[8:11], v90 offset:0x1200
	v_add_f32_dpp v0, v0, v0 row_half_mirror row_mask:0xf bank_mask:0xf bound_ctrl:1
	s_waitcnt lgkmcnt(5)
	ds_read2st64_b32 v[108:109], v89 offset0:200 offset1:201
	ds_read2st64_b64 v[100:103], v88 offset0:72 offset1:73
	v_add_f32_dpp v2, v0, v0 row_mirror row_mask:0xf bank_mask:0xf bound_ctrl:1
	v_add_f32_dpp v0, v0, v0 row_mirror row_mask:0xf bank_mask:0xf bound_ctrl:1
	s_nop 1
	v_permlane16_swap_b32_e32 v0, v2
	v_add_f32_e32 v0, v0, v2
	v_pk_fma_f32 v[52:53], v[104:105], v[0:1], v[54:55] op_sel_hi:[1,0,1]
	v_pk_mul_f32 v[118:119], v[52:53], v[112:113] op_sel_hi:[0,1]
	v_pk_fma_f32 v[118:119], v[52:53], v[114:115], v[118:119] op_sel:[1,0,0]
	v_pk_mul_f32 v[98:99], v[110:111], v[98:99] op_sel:[1,0]
	ds_read_b128 v[112:115], v90 offset:0x5400
	v_add_f32_dpp v118, v118, v118 quad_perm:[1,0,3,2] row_mask:0xf bank_mask:0xf bound_ctrl:1
	v_add_f32_dpp v119, v119, v119 quad_perm:[1,0,3,2] row_mask:0xf bank_mask:0xf bound_ctrl:1
	s_nop 0
	v_add_f32_dpp v118, v118, v118 quad_perm:[2,3,0,1] row_mask:0xf bank_mask:0xf bound_ctrl:1
	v_pk_fma_f32 v[54:55], v[52:53], v[96:97], v[98:99]
	ds_read_b128 v[96:99], v90 offset:0x1400
	v_add_f32_dpp v118, v118, v118 row_half_mirror row_mask:0xf bank_mask:0xf bound_ctrl:1
	s_waitcnt lgkmcnt(3)
	ds_write2_b32 v93, v1, v119 offset0:216 offset1:252
	v_add_f32_dpp v2, v118, v118 row_mirror row_mask:0xf bank_mask:0xf bound_ctrl:1
	v_add_f32_dpp v118, v118, v118 row_mirror row_mask:0xf bank_mask:0xf bound_ctrl:1
	s_nop 1
	v_permlane16_swap_b32_e32 v118, v2
	v_add_f32_e32 v118, v118, v2
	v_pk_fma_f32 v[52:53], v[106:107], v[118:119], v[54:55] op_sel_hi:[1,0,1]
	v_pk_mul_f32 v[0:1], v[52:53], v[120:121] op_sel_hi:[0,1]
	v_pk_fma_f32 v[0:1], v[52:53], v[122:123], v[0:1] op_sel:[1,0,0]
	v_pk_mul_f32 v[126:127], v[108:109], v[126:127] op_sel_hi:[0,1]
	ds_read_b128 v[120:123], v90 offset:0x5600
	v_add_f32_dpp v0, v0, v0 quad_perm:[1,0,3,2] row_mask:0xf bank_mask:0xf bound_ctrl:1
	v_add_f32_dpp v1, v1, v1 quad_perm:[1,0,3,2] row_mask:0xf bank_mask:0xf bound_ctrl:1
	v_add_u32_e32 v93, 0x480, v93
	v_add_f32_dpp v0, v0, v0 quad_perm:[2,3,0,1] row_mask:0xf bank_mask:0xf bound_ctrl:1
	v_pk_fma_f32 v[54:55], v[52:53], v[124:125], v[126:127]
	ds_read_b128 v[124:127], v90 offset:0x1600
	v_add_f32_dpp v0, v0, v0 row_half_mirror row_mask:0xf bank_mask:0xf bound_ctrl:1
	s_waitcnt lgkmcnt(5)
	ds_read2st64_b32 v[110:111], v89 offset0:202 offset1:203
	ds_read2st64_b64 v[104:107], v88 offset0:74 offset1:75
	v_add_f32_dpp v2, v0, v0 row_mirror row_mask:0xf bank_mask:0xf bound_ctrl:1
	v_add_f32_dpp v0, v0, v0 row_mirror row_mask:0xf bank_mask:0xf bound_ctrl:1
	s_nop 1
	v_permlane16_swap_b32_e32 v0, v2
	v_add_f32_e32 v0, v0, v2
	v_pk_fma_f32 v[52:53], v[100:101], v[0:1], v[54:55] op_sel_hi:[1,0,1]
	v_pk_mul_f32 v[118:119], v[52:53], v[4:5] op_sel_hi:[0,1]
	v_pk_fma_f32 v[118:119], v[52:53], v[6:7], v[118:119] op_sel:[1,0,0]
	v_pk_mul_f32 v[10:11], v[108:109], v[10:11] op_sel:[1,0]
	ds_read_b128 v[4:7], v90 offset:0x5800
	v_add_f32_dpp v118, v118, v118 quad_perm:[1,0,3,2] row_mask:0xf bank_mask:0xf bound_ctrl:1
	v_add_f32_dpp v119, v119, v119 quad_perm:[1,0,3,2] row_mask:0xf bank_mask:0xf bound_ctrl:1
	s_nop 0
	v_add_f32_dpp v118, v118, v118 quad_perm:[2,3,0,1] row_mask:0xf bank_mask:0xf bound_ctrl:1
	v_pk_fma_f32 v[54:55], v[52:53], v[8:9], v[10:11]
	ds_read_b128 v[8:11], v90 offset:0x1800
	v_add_f32_dpp v118, v118, v118 row_half_mirror row_mask:0xf bank_mask:0xf bound_ctrl:1
	s_waitcnt lgkmcnt(3)
	ds_write2_b32 v93, v1, v119 offset0:0 offset1:36
	v_add_f32_dpp v2, v118, v118 row_mirror row_mask:0xf bank_mask:0xf bound_ctrl:1
	v_add_f32_dpp v118, v118, v118 row_mirror row_mask:0xf bank_mask:0xf bound_ctrl:1
	s_nop 1
	v_permlane16_swap_b32_e32 v118, v2
	v_add_f32_e32 v118, v118, v2
	v_pk_fma_f32 v[52:53], v[102:103], v[118:119], v[54:55] op_sel_hi:[1,0,1]
	v_pk_mul_f32 v[0:1], v[52:53], v[112:113] op_sel_hi:[0,1]
	v_pk_fma_f32 v[0:1], v[52:53], v[114:115], v[0:1] op_sel:[1,0,0]
	v_pk_mul_f32 v[98:99], v[110:111], v[98:99] op_sel_hi:[0,1]
	ds_read_b128 v[112:115], v90 offset:0x5a00
	v_add_f32_dpp v0, v0, v0 quad_perm:[1,0,3,2] row_mask:0xf bank_mask:0xf bound_ctrl:1
	v_add_f32_dpp v1, v1, v1 quad_perm:[1,0,3,2] row_mask:0xf bank_mask:0xf bound_ctrl:1
	s_nop 0
	v_add_f32_dpp v0, v0, v0 quad_perm:[2,3,0,1] row_mask:0xf bank_mask:0xf bound_ctrl:1
	v_pk_fma_f32 v[54:55], v[52:53], v[96:97], v[98:99]
	ds_read_b128 v[96:99], v90 offset:0x1a00
	v_add_f32_dpp v0, v0, v0 row_half_mirror row_mask:0xf bank_mask:0xf bound_ctrl:1
	s_waitcnt lgkmcnt(5)
	ds_read2st64_b32 v[108:109], v89 offset0:204 offset1:205
	ds_read2st64_b64 v[100:103], v88 offset0:76 offset1:77
	v_add_f32_dpp v2, v0, v0 row_mirror row_mask:0xf bank_mask:0xf bound_ctrl:1
	v_add_f32_dpp v0, v0, v0 row_mirror row_mask:0xf bank_mask:0xf bound_ctrl:1
	s_nop 1
	v_permlane16_swap_b32_e32 v0, v2
	v_add_f32_e32 v0, v0, v2
	v_pk_fma_f32 v[52:53], v[104:105], v[0:1], v[54:55] op_sel_hi:[1,0,1]
	v_pk_mul_f32 v[118:119], v[52:53], v[120:121] op_sel_hi:[0,1]
	v_pk_fma_f32 v[118:119], v[52:53], v[122:123], v[118:119] op_sel:[1,0,0]
	v_pk_mul_f32 v[126:127], v[110:111], v[126:127] op_sel:[1,0]
	ds_read_b128 v[120:123], v90 offset:0x5c00
	v_add_f32_dpp v118, v118, v118 quad_perm:[1,0,3,2] row_mask:0xf bank_mask:0xf bound_ctrl:1
	v_add_f32_dpp v119, v119, v119 quad_perm:[1,0,3,2] row_mask:0xf bank_mask:0xf bound_ctrl:1
	s_nop 0
	v_add_f32_dpp v118, v118, v118 quad_perm:[2,3,0,1] row_mask:0xf bank_mask:0xf bound_ctrl:1
	v_pk_fma_f32 v[54:55], v[52:53], v[124:125], v[126:127]
	ds_read_b128 v[124:127], v90 offset:0x1c00
	v_add_f32_dpp v118, v118, v118 row_half_mirror row_mask:0xf bank_mask:0xf bound_ctrl:1
	s_waitcnt lgkmcnt(3)
	ds_write2_b32 v93, v1, v119 offset0:72 offset1:108
	v_add_f32_dpp v2, v118, v118 row_mirror row_mask:0xf bank_mask:0xf bound_ctrl:1
	v_add_f32_dpp v118, v118, v118 row_mirror row_mask:0xf bank_mask:0xf bound_ctrl:1
	s_nop 1
	v_permlane16_swap_b32_e32 v118, v2
	v_add_f32_e32 v118, v118, v2
	v_pk_fma_f32 v[52:53], v[106:107], v[118:119], v[54:55] op_sel_hi:[1,0,1]
	v_pk_mul_f32 v[0:1], v[52:53], v[4:5] op_sel_hi:[0,1]
	v_pk_fma_f32 v[0:1], v[52:53], v[6:7], v[0:1] op_sel:[1,0,0]
	v_pk_mul_f32 v[10:11], v[108:109], v[10:11] op_sel_hi:[0,1]
	ds_read_b128 v[4:7], v90 offset:0x5e00
	v_add_f32_dpp v0, v0, v0 quad_perm:[1,0,3,2] row_mask:0xf bank_mask:0xf bound_ctrl:1
	v_add_f32_dpp v1, v1, v1 quad_perm:[1,0,3,2] row_mask:0xf bank_mask:0xf bound_ctrl:1
	s_nop 0
	v_add_f32_dpp v0, v0, v0 quad_perm:[2,3,0,1] row_mask:0xf bank_mask:0xf bound_ctrl:1
	v_pk_fma_f32 v[54:55], v[52:53], v[8:9], v[10:11]
	ds_read_b128 v[8:11], v90 offset:0x1e00
	v_add_f32_dpp v0, v0, v0 row_half_mirror row_mask:0xf bank_mask:0xf bound_ctrl:1
	s_waitcnt lgkmcnt(5)
	ds_read2st64_b32 v[110:111], v89 offset0:206 offset1:207
	ds_read2st64_b64 v[104:107], v88 offset0:78 offset1:79
	v_add_f32_dpp v2, v0, v0 row_mirror row_mask:0xf bank_mask:0xf bound_ctrl:1
	v_add_f32_dpp v0, v0, v0 row_mirror row_mask:0xf bank_mask:0xf bound_ctrl:1
	s_nop 1
	v_permlane16_swap_b32_e32 v0, v2
	v_add_f32_e32 v0, v0, v2
	v_pk_fma_f32 v[52:53], v[100:101], v[0:1], v[54:55] op_sel_hi:[1,0,1]
	v_pk_mul_f32 v[118:119], v[52:53], v[112:113] op_sel_hi:[0,1]
	v_pk_fma_f32 v[118:119], v[52:53], v[114:115], v[118:119] op_sel:[1,0,0]
	v_pk_mul_f32 v[98:99], v[108:109], v[98:99] op_sel:[1,0]
	ds_read_b128 v[112:115], v90 offset:0x6000
	v_add_f32_dpp v118, v118, v118 quad_perm:[1,0,3,2] row_mask:0xf bank_mask:0xf bound_ctrl:1
	v_add_f32_dpp v119, v119, v119 quad_perm:[1,0,3,2] row_mask:0xf bank_mask:0xf bound_ctrl:1
	s_nop 0
	v_add_f32_dpp v118, v118, v118 quad_perm:[2,3,0,1] row_mask:0xf bank_mask:0xf bound_ctrl:1
	v_pk_fma_f32 v[54:55], v[52:53], v[96:97], v[98:99]
	ds_read_b128 v[96:99], v90 offset:0x2000
	v_add_f32_dpp v118, v118, v118 row_half_mirror row_mask:0xf bank_mask:0xf bound_ctrl:1
	s_waitcnt lgkmcnt(3)
	ds_write2_b32 v93, v1, v119 offset0:144 offset1:180
	v_add_f32_dpp v2, v118, v118 row_mirror row_mask:0xf bank_mask:0xf bound_ctrl:1
	v_add_f32_dpp v118, v118, v118 row_mirror row_mask:0xf bank_mask:0xf bound_ctrl:1
	s_nop 1
	v_permlane16_swap_b32_e32 v118, v2
	v_add_f32_e32 v118, v118, v2
	v_pk_fma_f32 v[52:53], v[102:103], v[118:119], v[54:55] op_sel_hi:[1,0,1]
	v_pk_mul_f32 v[0:1], v[52:53], v[120:121] op_sel_hi:[0,1]
	v_pk_fma_f32 v[0:1], v[52:53], v[122:123], v[0:1] op_sel:[1,0,0]
	v_pk_mul_f32 v[126:127], v[110:111], v[126:127] op_sel_hi:[0,1]
	ds_read_b128 v[120:123], v90 offset:0x6200
	v_add_f32_dpp v0, v0, v0 quad_perm:[1,0,3,2] row_mask:0xf bank_mask:0xf bound_ctrl:1
	v_add_f32_dpp v1, v1, v1 quad_perm:[1,0,3,2] row_mask:0xf bank_mask:0xf bound_ctrl:1
	s_nop 0
	v_add_f32_dpp v0, v0, v0 quad_perm:[2,3,0,1] row_mask:0xf bank_mask:0xf bound_ctrl:1
	v_pk_fma_f32 v[54:55], v[52:53], v[124:125], v[126:127]
	ds_read_b128 v[124:127], v90 offset:0x2200
	v_add_f32_dpp v0, v0, v0 row_half_mirror row_mask:0xf bank_mask:0xf bound_ctrl:1
	s_waitcnt lgkmcnt(5)
	ds_read2st64_b32 v[108:109], v89 offset0:208 offset1:209
	ds_read2st64_b64 v[100:103], v88 offset0:80 offset1:81
	v_add_f32_dpp v2, v0, v0 row_mirror row_mask:0xf bank_mask:0xf bound_ctrl:1
	v_add_f32_dpp v0, v0, v0 row_mirror row_mask:0xf bank_mask:0xf bound_ctrl:1
	s_nop 1
	v_permlane16_swap_b32_e32 v0, v2
	v_add_f32_e32 v0, v0, v2
	v_pk_fma_f32 v[52:53], v[104:105], v[0:1], v[54:55] op_sel_hi:[1,0,1]
	v_pk_mul_f32 v[118:119], v[52:53], v[4:5] op_sel_hi:[0,1]
	v_pk_fma_f32 v[118:119], v[52:53], v[6:7], v[118:119] op_sel:[1,0,0]
	v_pk_mul_f32 v[10:11], v[110:111], v[10:11] op_sel:[1,0]
	ds_read_b128 v[4:7], v90 offset:0x6400
	v_add_f32_dpp v118, v118, v118 quad_perm:[1,0,3,2] row_mask:0xf bank_mask:0xf bound_ctrl:1
	v_add_f32_dpp v119, v119, v119 quad_perm:[1,0,3,2] row_mask:0xf bank_mask:0xf bound_ctrl:1
	s_nop 0
	v_add_f32_dpp v118, v118, v118 quad_perm:[2,3,0,1] row_mask:0xf bank_mask:0xf bound_ctrl:1
	v_pk_fma_f32 v[54:55], v[52:53], v[8:9], v[10:11]
	ds_read_b128 v[8:11], v90 offset:0x2400
	v_add_f32_dpp v118, v118, v118 row_half_mirror row_mask:0xf bank_mask:0xf bound_ctrl:1
	s_waitcnt lgkmcnt(3)
	ds_write2_b32 v93, v1, v119 offset0:216 offset1:252
	v_add_f32_dpp v2, v118, v118 row_mirror row_mask:0xf bank_mask:0xf bound_ctrl:1
	v_add_f32_dpp v118, v118, v118 row_mirror row_mask:0xf bank_mask:0xf bound_ctrl:1
	s_nop 1
	v_permlane16_swap_b32_e32 v118, v2
	v_add_f32_e32 v118, v118, v2
	v_pk_fma_f32 v[52:53], v[106:107], v[118:119], v[54:55] op_sel_hi:[1,0,1]
	s_cmp_eq_u32 s88, 0x800000
	s_cbranch_scc1 .LBB0_684
	v_pk_mul_f32 v[0:1], v[52:53], v[112:113] op_sel_hi:[0,1]
	v_pk_fma_f32 v[0:1], v[52:53], v[114:115], v[0:1] op_sel:[1,0,0]
	v_pk_mul_f32 v[98:99], v[108:109], v[98:99] op_sel_hi:[0,1]
	ds_read_b128 v[112:115], v90 offset:0x6600
	v_add_f32_dpp v0, v0, v0 quad_perm:[1,0,3,2] row_mask:0xf bank_mask:0xf bound_ctrl:1
	v_add_f32_dpp v1, v1, v1 quad_perm:[1,0,3,2] row_mask:0xf bank_mask:0xf bound_ctrl:1
	v_add_u32_e32 v93, 0x480, v93
	v_add_f32_dpp v0, v0, v0 quad_perm:[2,3,0,1] row_mask:0xf bank_mask:0xf bound_ctrl:1
	v_pk_fma_f32 v[54:55], v[52:53], v[96:97], v[98:99]
	ds_read_b128 v[96:99], v90 offset:0x2600
	v_add_f32_dpp v0, v0, v0 row_half_mirror row_mask:0xf bank_mask:0xf bound_ctrl:1
	s_waitcnt lgkmcnt(5)
	ds_read2st64_b32 v[110:111], v89 offset0:210 offset1:211
	ds_read2st64_b64 v[104:107], v88 offset0:82 offset1:83
	v_add_f32_dpp v2, v0, v0 row_mirror row_mask:0xf bank_mask:0xf bound_ctrl:1
	v_add_f32_dpp v0, v0, v0 row_mirror row_mask:0xf bank_mask:0xf bound_ctrl:1
	s_nop 1
	v_permlane16_swap_b32_e32 v0, v2
	v_add_f32_e32 v0, v0, v2
	v_pk_fma_f32 v[52:53], v[100:101], v[0:1], v[54:55] op_sel_hi:[1,0,1]
	v_pk_mul_f32 v[118:119], v[52:53], v[120:121] op_sel_hi:[0,1]
	v_pk_fma_f32 v[118:119], v[52:53], v[122:123], v[118:119] op_sel:[1,0,0]
	v_pk_mul_f32 v[126:127], v[108:109], v[126:127] op_sel:[1,0]
	ds_read_b128 v[120:123], v90 offset:0x6800
	v_add_f32_dpp v118, v118, v118 quad_perm:[1,0,3,2] row_mask:0xf bank_mask:0xf bound_ctrl:1
	v_add_f32_dpp v119, v119, v119 quad_perm:[1,0,3,2] row_mask:0xf bank_mask:0xf bound_ctrl:1
	s_nop 0
	v_add_f32_dpp v118, v118, v118 quad_perm:[2,3,0,1] row_mask:0xf bank_mask:0xf bound_ctrl:1
	v_pk_fma_f32 v[54:55], v[52:53], v[124:125], v[126:127]
	ds_read_b128 v[124:127], v90 offset:0x2800
	v_add_f32_dpp v118, v118, v118 row_half_mirror row_mask:0xf bank_mask:0xf bound_ctrl:1
	s_waitcnt lgkmcnt(3)
	ds_write2_b32 v93, v1, v119 offset0:0 offset1:36
	v_add_f32_dpp v2, v118, v118 row_mirror row_mask:0xf bank_mask:0xf bound_ctrl:1
	v_add_f32_dpp v118, v118, v118 row_mirror row_mask:0xf bank_mask:0xf bound_ctrl:1
	s_nop 1
	v_permlane16_swap_b32_e32 v118, v2
	v_add_f32_e32 v118, v118, v2
	v_pk_fma_f32 v[52:53], v[102:103], v[118:119], v[54:55] op_sel_hi:[1,0,1]
	v_pk_mul_f32 v[0:1], v[52:53], v[4:5] op_sel_hi:[0,1]
	v_pk_fma_f32 v[0:1], v[52:53], v[6:7], v[0:1] op_sel:[1,0,0]
	v_pk_mul_f32 v[10:11], v[110:111], v[10:11] op_sel_hi:[0,1]
	ds_read_b128 v[4:7], v90 offset:0x6a00
	v_add_f32_dpp v0, v0, v0 quad_perm:[1,0,3,2] row_mask:0xf bank_mask:0xf bound_ctrl:1
	v_add_f32_dpp v1, v1, v1 quad_perm:[1,0,3,2] row_mask:0xf bank_mask:0xf bound_ctrl:1
	s_nop 0
	v_add_f32_dpp v0, v0, v0 quad_perm:[2,3,0,1] row_mask:0xf bank_mask:0xf bound_ctrl:1
	v_pk_fma_f32 v[54:55], v[52:53], v[8:9], v[10:11]
	ds_read_b128 v[8:11], v90 offset:0x2a00
	v_add_f32_dpp v0, v0, v0 row_half_mirror row_mask:0xf bank_mask:0xf bound_ctrl:1
	s_waitcnt lgkmcnt(5)
	ds_read2st64_b32 v[108:109], v89 offset0:212 offset1:213
	ds_read2st64_b64 v[100:103], v88 offset0:84 offset1:85
	v_add_f32_dpp v2, v0, v0 row_mirror row_mask:0xf bank_mask:0xf bound_ctrl:1
	v_add_f32_dpp v0, v0, v0 row_mirror row_mask:0xf bank_mask:0xf bound_ctrl:1
	s_nop 1
	v_permlane16_swap_b32_e32 v0, v2
	v_add_f32_e32 v0, v0, v2
	v_pk_fma_f32 v[52:53], v[104:105], v[0:1], v[54:55] op_sel_hi:[1,0,1]
	v_pk_mul_f32 v[118:119], v[52:53], v[112:113] op_sel_hi:[0,1]
	v_pk_fma_f32 v[118:119], v[52:53], v[114:115], v[118:119] op_sel:[1,0,0]
	v_pk_mul_f32 v[98:99], v[110:111], v[98:99] op_sel:[1,0]
	ds_read_b128 v[112:115], v90 offset:0x6c00
	v_add_f32_dpp v118, v118, v118 quad_perm:[1,0,3,2] row_mask:0xf bank_mask:0xf bound_ctrl:1
	v_add_f32_dpp v119, v119, v119 quad_perm:[1,0,3,2] row_mask:0xf bank_mask:0xf bound_ctrl:1
	s_nop 0
	v_add_f32_dpp v118, v118, v118 quad_perm:[2,3,0,1] row_mask:0xf bank_mask:0xf bound_ctrl:1
	v_pk_fma_f32 v[54:55], v[52:53], v[96:97], v[98:99]
	ds_read_b128 v[96:99], v90 offset:0x2c00
	v_add_f32_dpp v118, v118, v118 row_half_mirror row_mask:0xf bank_mask:0xf bound_ctrl:1
	s_waitcnt lgkmcnt(3)
	ds_write2_b32 v93, v1, v119 offset0:72 offset1:108
	v_add_f32_dpp v2, v118, v118 row_mirror row_mask:0xf bank_mask:0xf bound_ctrl:1
	v_add_f32_dpp v118, v118, v118 row_mirror row_mask:0xf bank_mask:0xf bound_ctrl:1
	s_nop 1
	v_permlane16_swap_b32_e32 v118, v2
	v_add_f32_e32 v118, v118, v2
	v_pk_fma_f32 v[52:53], v[106:107], v[118:119], v[54:55] op_sel_hi:[1,0,1]
	v_pk_mul_f32 v[0:1], v[52:53], v[120:121] op_sel_hi:[0,1]
	v_pk_fma_f32 v[0:1], v[52:53], v[122:123], v[0:1] op_sel:[1,0,0]
	v_pk_mul_f32 v[126:127], v[108:109], v[126:127] op_sel_hi:[0,1]
	ds_read_b128 v[120:123], v90 offset:0x6e00
	v_add_f32_dpp v0, v0, v0 quad_perm:[1,0,3,2] row_mask:0xf bank_mask:0xf bound_ctrl:1
	v_add_f32_dpp v1, v1, v1 quad_perm:[1,0,3,2] row_mask:0xf bank_mask:0xf bound_ctrl:1
	s_nop 0
	v_add_f32_dpp v0, v0, v0 quad_perm:[2,3,0,1] row_mask:0xf bank_mask:0xf bound_ctrl:1
	v_pk_fma_f32 v[54:55], v[52:53], v[124:125], v[126:127]
	ds_read_b128 v[124:127], v90 offset:0x2e00
	v_add_f32_dpp v0, v0, v0 row_half_mirror row_mask:0xf bank_mask:0xf bound_ctrl:1
	s_waitcnt lgkmcnt(5)
	ds_read2st64_b32 v[110:111], v89 offset0:214 offset1:215
	ds_read2st64_b64 v[104:107], v88 offset0:86 offset1:87
	v_add_f32_dpp v2, v0, v0 row_mirror row_mask:0xf bank_mask:0xf bound_ctrl:1
	v_add_f32_dpp v0, v0, v0 row_mirror row_mask:0xf bank_mask:0xf bound_ctrl:1
	s_nop 1
	v_permlane16_swap_b32_e32 v0, v2
	v_add_f32_e32 v0, v0, v2
	v_pk_fma_f32 v[52:53], v[100:101], v[0:1], v[54:55] op_sel_hi:[1,0,1]
	v_pk_mul_f32 v[118:119], v[52:53], v[4:5] op_sel_hi:[0,1]
	v_pk_fma_f32 v[118:119], v[52:53], v[6:7], v[118:119] op_sel:[1,0,0]
	v_pk_mul_f32 v[10:11], v[108:109], v[10:11] op_sel:[1,0]
	ds_read_b128 v[4:7], v90 offset:0x7000
	v_add_f32_dpp v118, v118, v118 quad_perm:[1,0,3,2] row_mask:0xf bank_mask:0xf bound_ctrl:1
	v_add_f32_dpp v119, v119, v119 quad_perm:[1,0,3,2] row_mask:0xf bank_mask:0xf bound_ctrl:1
	s_nop 0
	v_add_f32_dpp v118, v118, v118 quad_perm:[2,3,0,1] row_mask:0xf bank_mask:0xf bound_ctrl:1
	v_pk_fma_f32 v[54:55], v[52:53], v[8:9], v[10:11]
	ds_read_b128 v[8:11], v90 offset:0x3000
	v_add_f32_dpp v118, v118, v118 row_half_mirror row_mask:0xf bank_mask:0xf bound_ctrl:1
	s_waitcnt lgkmcnt(3)
	ds_write2_b32 v93, v1, v119 offset0:144 offset1:180
	v_add_f32_dpp v2, v118, v118 row_mirror row_mask:0xf bank_mask:0xf bound_ctrl:1
	v_add_f32_dpp v118, v118, v118 row_mirror row_mask:0xf bank_mask:0xf bound_ctrl:1
	s_nop 1
	v_permlane16_swap_b32_e32 v118, v2
	v_add_f32_e32 v118, v118, v2
	v_pk_fma_f32 v[52:53], v[102:103], v[118:119], v[54:55] op_sel_hi:[1,0,1]
	v_pk_mul_f32 v[0:1], v[52:53], v[112:113] op_sel_hi:[0,1]
	v_pk_fma_f32 v[0:1], v[52:53], v[114:115], v[0:1] op_sel:[1,0,0]
	v_pk_mul_f32 v[98:99], v[110:111], v[98:99] op_sel_hi:[0,1]
	ds_read_b128 v[112:115], v90 offset:0x7200
	v_add_f32_dpp v0, v0, v0 quad_perm:[1,0,3,2] row_mask:0xf bank_mask:0xf bound_ctrl:1
	v_add_f32_dpp v1, v1, v1 quad_perm:[1,0,3,2] row_mask:0xf bank_mask:0xf bound_ctrl:1
	s_nop 0
	v_add_f32_dpp v0, v0, v0 quad_perm:[2,3,0,1] row_mask:0xf bank_mask:0xf bound_ctrl:1
	v_pk_fma_f32 v[54:55], v[52:53], v[96:97], v[98:99]
	ds_read_b128 v[96:99], v90 offset:0x3200
	v_add_f32_dpp v0, v0, v0 row_half_mirror row_mask:0xf bank_mask:0xf bound_ctrl:1
	s_waitcnt lgkmcnt(5)
	ds_read2st64_b32 v[108:109], v89 offset0:216 offset1:217
	ds_read2st64_b64 v[100:103], v88 offset0:88 offset1:89
	v_add_f32_dpp v2, v0, v0 row_mirror row_mask:0xf bank_mask:0xf bound_ctrl:1
	v_add_f32_dpp v0, v0, v0 row_mirror row_mask:0xf bank_mask:0xf bound_ctrl:1
	s_nop 1
	v_permlane16_swap_b32_e32 v0, v2
	v_add_f32_e32 v0, v0, v2
	v_pk_fma_f32 v[52:53], v[104:105], v[0:1], v[54:55] op_sel_hi:[1,0,1]
	v_pk_mul_f32 v[118:119], v[52:53], v[120:121] op_sel_hi:[0,1]
	v_pk_fma_f32 v[118:119], v[52:53], v[122:123], v[118:119] op_sel:[1,0,0]
	v_pk_mul_f32 v[126:127], v[110:111], v[126:127] op_sel:[1,0]
	ds_read_b128 v[120:123], v90 offset:0x7400
	v_add_f32_dpp v118, v118, v118 quad_perm:[1,0,3,2] row_mask:0xf bank_mask:0xf bound_ctrl:1
	v_add_f32_dpp v119, v119, v119 quad_perm:[1,0,3,2] row_mask:0xf bank_mask:0xf bound_ctrl:1
	s_nop 0
	v_add_f32_dpp v118, v118, v118 quad_perm:[2,3,0,1] row_mask:0xf bank_mask:0xf bound_ctrl:1
	v_pk_fma_f32 v[54:55], v[52:53], v[124:125], v[126:127]
	ds_read_b128 v[124:127], v90 offset:0x3400
	v_add_f32_dpp v118, v118, v118 row_half_mirror row_mask:0xf bank_mask:0xf bound_ctrl:1
	s_waitcnt lgkmcnt(3)
	ds_write2_b32 v93, v1, v119 offset0:216 offset1:252
	v_add_f32_dpp v2, v118, v118 row_mirror row_mask:0xf bank_mask:0xf bound_ctrl:1
	v_add_f32_dpp v118, v118, v118 row_mirror row_mask:0xf bank_mask:0xf bound_ctrl:1
	s_nop 1
	v_permlane16_swap_b32_e32 v118, v2
	v_add_f32_e32 v118, v118, v2
	v_pk_fma_f32 v[52:53], v[106:107], v[118:119], v[54:55] op_sel_hi:[1,0,1]
	v_pk_mul_f32 v[0:1], v[52:53], v[4:5] op_sel_hi:[0,1]
	v_pk_fma_f32 v[0:1], v[52:53], v[6:7], v[0:1] op_sel:[1,0,0]
	v_pk_mul_f32 v[10:11], v[108:109], v[10:11] op_sel_hi:[0,1]
	ds_read_b128 v[4:7], v90 offset:0x7600
	v_add_f32_dpp v0, v0, v0 quad_perm:[1,0,3,2] row_mask:0xf bank_mask:0xf bound_ctrl:1
	v_add_f32_dpp v1, v1, v1 quad_perm:[1,0,3,2] row_mask:0xf bank_mask:0xf bound_ctrl:1
	v_add_u32_e32 v93, 0x480, v93
	v_add_f32_dpp v0, v0, v0 quad_perm:[2,3,0,1] row_mask:0xf bank_mask:0xf bound_ctrl:1
	v_pk_fma_f32 v[54:55], v[52:53], v[8:9], v[10:11]
	ds_read_b128 v[8:11], v90 offset:0x3600
	v_add_f32_dpp v0, v0, v0 row_half_mirror row_mask:0xf bank_mask:0xf bound_ctrl:1
	s_waitcnt lgkmcnt(5)
	ds_read2st64_b32 v[110:111], v89 offset0:218 offset1:219
	ds_read2st64_b64 v[104:107], v88 offset0:90 offset1:91
	v_add_f32_dpp v2, v0, v0 row_mirror row_mask:0xf bank_mask:0xf bound_ctrl:1
	v_add_f32_dpp v0, v0, v0 row_mirror row_mask:0xf bank_mask:0xf bound_ctrl:1
	s_nop 1
	v_permlane16_swap_b32_e32 v0, v2
	v_add_f32_e32 v0, v0, v2
	v_pk_fma_f32 v[52:53], v[100:101], v[0:1], v[54:55] op_sel_hi:[1,0,1]
	v_pk_mul_f32 v[118:119], v[52:53], v[112:113] op_sel_hi:[0,1]
	v_pk_fma_f32 v[118:119], v[52:53], v[114:115], v[118:119] op_sel:[1,0,0]
	v_pk_mul_f32 v[98:99], v[108:109], v[98:99] op_sel:[1,0]
	ds_read_b128 v[112:115], v90 offset:0x7800
	v_add_f32_dpp v118, v118, v118 quad_perm:[1,0,3,2] row_mask:0xf bank_mask:0xf bound_ctrl:1
	v_add_f32_dpp v119, v119, v119 quad_perm:[1,0,3,2] row_mask:0xf bank_mask:0xf bound_ctrl:1
	s_nop 0
	v_add_f32_dpp v118, v118, v118 quad_perm:[2,3,0,1] row_mask:0xf bank_mask:0xf bound_ctrl:1
	v_pk_fma_f32 v[54:55], v[52:53], v[96:97], v[98:99]
	ds_read_b128 v[96:99], v90 offset:0x3800
	v_add_f32_dpp v118, v118, v118 row_half_mirror row_mask:0xf bank_mask:0xf bound_ctrl:1
	s_waitcnt lgkmcnt(3)
	ds_write2_b32 v93, v1, v119 offset0:0 offset1:36
	v_add_f32_dpp v2, v118, v118 row_mirror row_mask:0xf bank_mask:0xf bound_ctrl:1
	v_add_f32_dpp v118, v118, v118 row_mirror row_mask:0xf bank_mask:0xf bound_ctrl:1
	s_nop 1
	v_permlane16_swap_b32_e32 v118, v2
	v_add_f32_e32 v118, v118, v2
	v_pk_fma_f32 v[52:53], v[102:103], v[118:119], v[54:55] op_sel_hi:[1,0,1]
	v_pk_mul_f32 v[0:1], v[52:53], v[120:121] op_sel_hi:[0,1]
	v_pk_fma_f32 v[0:1], v[52:53], v[122:123], v[0:1] op_sel:[1,0,0]
	v_pk_mul_f32 v[126:127], v[110:111], v[126:127] op_sel_hi:[0,1]
	ds_read_b128 v[120:123], v90 offset:0x7a00
	v_add_f32_dpp v0, v0, v0 quad_perm:[1,0,3,2] row_mask:0xf bank_mask:0xf bound_ctrl:1
	v_add_f32_dpp v1, v1, v1 quad_perm:[1,0,3,2] row_mask:0xf bank_mask:0xf bound_ctrl:1
	s_nop 0
	v_add_f32_dpp v0, v0, v0 quad_perm:[2,3,0,1] row_mask:0xf bank_mask:0xf bound_ctrl:1
	v_pk_fma_f32 v[54:55], v[52:53], v[124:125], v[126:127]
	ds_read_b128 v[124:127], v90 offset:0x3a00
	v_add_f32_dpp v0, v0, v0 row_half_mirror row_mask:0xf bank_mask:0xf bound_ctrl:1
	s_waitcnt lgkmcnt(5)
	ds_read2st64_b32 v[108:109], v89 offset0:220 offset1:221
	ds_read2st64_b64 v[100:103], v88 offset0:92 offset1:93
	v_add_f32_dpp v2, v0, v0 row_mirror row_mask:0xf bank_mask:0xf bound_ctrl:1
	v_add_f32_dpp v0, v0, v0 row_mirror row_mask:0xf bank_mask:0xf bound_ctrl:1
	s_nop 1
	v_permlane16_swap_b32_e32 v0, v2
	v_add_f32_e32 v0, v0, v2
	v_pk_fma_f32 v[52:53], v[104:105], v[0:1], v[54:55] op_sel_hi:[1,0,1]
	v_pk_mul_f32 v[118:119], v[52:53], v[4:5] op_sel_hi:[0,1]
	v_pk_fma_f32 v[118:119], v[52:53], v[6:7], v[118:119] op_sel:[1,0,0]
	v_pk_mul_f32 v[10:11], v[110:111], v[10:11] op_sel:[1,0]
	ds_read_b128 v[4:7], v90 offset:0x7c00
	v_add_f32_dpp v118, v118, v118 quad_perm:[1,0,3,2] row_mask:0xf bank_mask:0xf bound_ctrl:1
	v_add_f32_dpp v119, v119, v119 quad_perm:[1,0,3,2] row_mask:0xf bank_mask:0xf bound_ctrl:1
	s_nop 0
	v_add_f32_dpp v118, v118, v118 quad_perm:[2,3,0,1] row_mask:0xf bank_mask:0xf bound_ctrl:1
	v_pk_fma_f32 v[54:55], v[52:53], v[8:9], v[10:11]
	ds_read_b128 v[8:11], v90 offset:0x3c00
	v_add_f32_dpp v118, v118, v118 row_half_mirror row_mask:0xf bank_mask:0xf bound_ctrl:1
	s_waitcnt lgkmcnt(3)
	ds_write2_b32 v93, v1, v119 offset0:72 offset1:108
	v_add_f32_dpp v2, v118, v118 row_mirror row_mask:0xf bank_mask:0xf bound_ctrl:1
	v_add_f32_dpp v118, v118, v118 row_mirror row_mask:0xf bank_mask:0xf bound_ctrl:1
	s_nop 1
	v_permlane16_swap_b32_e32 v118, v2
	v_add_f32_e32 v118, v118, v2
	v_pk_fma_f32 v[52:53], v[106:107], v[118:119], v[54:55] op_sel_hi:[1,0,1]
	v_pk_mul_f32 v[0:1], v[52:53], v[112:113] op_sel_hi:[0,1]
	v_pk_fma_f32 v[0:1], v[52:53], v[114:115], v[0:1] op_sel:[1,0,0]
	v_pk_mul_f32 v[98:99], v[108:109], v[98:99] op_sel_hi:[0,1]
	ds_read_b128 v[112:115], v90 offset:0x7e00
	v_add_f32_dpp v0, v0, v0 quad_perm:[1,0,3,2] row_mask:0xf bank_mask:0xf bound_ctrl:1
	v_add_f32_dpp v1, v1, v1 quad_perm:[1,0,3,2] row_mask:0xf bank_mask:0xf bound_ctrl:1
	s_nop 0
	v_add_f32_dpp v0, v0, v0 quad_perm:[2,3,0,1] row_mask:0xf bank_mask:0xf bound_ctrl:1
	v_pk_fma_f32 v[54:55], v[52:53], v[96:97], v[98:99]
	ds_read_b128 v[96:99], v90 offset:0x3e00
	v_add_f32_dpp v0, v0, v0 row_half_mirror row_mask:0xf bank_mask:0xf bound_ctrl:1
	s_waitcnt lgkmcnt(5)
	ds_read2st64_b32 v[110:111], v89 offset0:222 offset1:223
	ds_read2st64_b64 v[104:107], v88 offset0:94 offset1:95
	v_add_f32_dpp v2, v0, v0 row_mirror row_mask:0xf bank_mask:0xf bound_ctrl:1
	v_add_f32_dpp v0, v0, v0 row_mirror row_mask:0xf bank_mask:0xf bound_ctrl:1
	s_nop 1
	v_permlane16_swap_b32_e32 v0, v2
	v_add_f32_e32 v0, v0, v2
	v_pk_fma_f32 v[52:53], v[100:101], v[0:1], v[54:55] op_sel_hi:[1,0,1]
	v_pk_mul_f32 v[118:119], v[52:53], v[120:121] op_sel_hi:[0,1]
	v_pk_fma_f32 v[118:119], v[52:53], v[122:123], v[118:119] op_sel:[1,0,0]
	v_pk_mul_f32 v[126:127], v[108:109], v[126:127] op_sel:[1,0]
	s_nop 0
	v_add_f32_dpp v118, v118, v118 quad_perm:[1,0,3,2] row_mask:0xf bank_mask:0xf bound_ctrl:1
	v_add_f32_dpp v119, v119, v119 quad_perm:[1,0,3,2] row_mask:0xf bank_mask:0xf bound_ctrl:1
	s_nop 0
	v_add_f32_dpp v118, v118, v118 quad_perm:[2,3,0,1] row_mask:0xf bank_mask:0xf bound_ctrl:1
	v_pk_fma_f32 v[54:55], v[52:53], v[124:125], v[126:127]
	s_nop 0
	v_add_f32_dpp v118, v118, v118 row_half_mirror row_mask:0xf bank_mask:0xf bound_ctrl:1
	s_waitcnt lgkmcnt(1)
	ds_write2_b32 v93, v1, v119 offset0:144 offset1:180
	v_add_f32_dpp v2, v118, v118 row_mirror row_mask:0xf bank_mask:0xf bound_ctrl:1
	v_add_f32_dpp v118, v118, v118 row_mirror row_mask:0xf bank_mask:0xf bound_ctrl:1
	s_nop 1
	v_permlane16_swap_b32_e32 v118, v2
	v_add_f32_e32 v118, v118, v2
	v_pk_fma_f32 v[52:53], v[102:103], v[118:119], v[54:55] op_sel_hi:[1,0,1]
	v_pk_mul_f32 v[0:1], v[52:53], v[4:5] op_sel_hi:[0,1]
	v_pk_fma_f32 v[0:1], v[52:53], v[6:7], v[0:1] op_sel:[1,0,0]
	v_pk_mul_f32 v[10:11], v[110:111], v[10:11] op_sel_hi:[0,1]
	s_nop 0
	v_add_f32_dpp v0, v0, v0 quad_perm:[1,0,3,2] row_mask:0xf bank_mask:0xf bound_ctrl:1
	v_add_f32_dpp v1, v1, v1 quad_perm:[1,0,3,2] row_mask:0xf bank_mask:0xf bound_ctrl:1
	s_nop 0
	v_add_f32_dpp v0, v0, v0 quad_perm:[2,3,0,1] row_mask:0xf bank_mask:0xf bound_ctrl:1
	v_pk_fma_f32 v[54:55], v[52:53], v[8:9], v[10:11]
	s_nop 0
	v_add_f32_dpp v0, v0, v0 row_half_mirror row_mask:0xf bank_mask:0xf bound_ctrl:1
	s_waitcnt lgkmcnt(1)
	s_nop 0
	v_add_f32_dpp v2, v0, v0 row_mirror row_mask:0xf bank_mask:0xf bound_ctrl:1
	v_add_f32_dpp v0, v0, v0 row_mirror row_mask:0xf bank_mask:0xf bound_ctrl:1
	s_nop 1
	v_permlane16_swap_b32_e32 v0, v2
	v_add_f32_e32 v0, v0, v2
	v_pk_fma_f32 v[52:53], v[104:105], v[0:1], v[54:55] op_sel_hi:[1,0,1]
	v_pk_mul_f32 v[118:119], v[52:53], v[112:113] op_sel_hi:[0,1]
	v_pk_fma_f32 v[118:119], v[52:53], v[114:115], v[118:119] op_sel:[1,0,0]
	v_pk_mul_f32 v[98:99], v[110:111], v[98:99] op_sel:[1,0]
	s_nop 0
	v_add_f32_dpp v118, v118, v118 quad_perm:[1,0,3,2] row_mask:0xf bank_mask:0xf bound_ctrl:1
	v_add_f32_dpp v119, v119, v119 quad_perm:[1,0,3,2] row_mask:0xf bank_mask:0xf bound_ctrl:1
	s_nop 0
	v_add_f32_dpp v118, v118, v118 quad_perm:[2,3,0,1] row_mask:0xf bank_mask:0xf bound_ctrl:1
	v_pk_fma_f32 v[54:55], v[52:53], v[96:97], v[98:99]
	s_nop 0
	v_add_f32_dpp v118, v118, v118 row_half_mirror row_mask:0xf bank_mask:0xf bound_ctrl:1
	s_nop 0
	ds_write2_b32 v93, v1, v119 offset0:216 offset1:252
	v_add_f32_dpp v2, v118, v118 row_mirror row_mask:0xf bank_mask:0xf bound_ctrl:1
	v_add_f32_dpp v118, v118, v118 row_mirror row_mask:0xf bank_mask:0xf bound_ctrl:1
	s_nop 1
	v_permlane16_swap_b32_e32 v118, v2
	v_add_f32_e32 v118, v118, v2
	v_pk_fma_f32 v[52:53], v[106:107], v[118:119], v[54:55] op_sel_hi:[1,0,1]
